# grid-barrier spin loops poll without s_sleep (lower release-detection latency)
# baseline (speedup 1.0000x reference)
; __global__ void __launch_bounds__(NTHR, 2) fwd_megakernel(Args a) {
;     ...
;     if (lo < 0) grid.sync();
.LBB0_14:
	global_load_dword v2, v0, s[4:5] offset:32 sc1
	s_waitcnt vmcnt(0)
	v_and_b32_e32 v2, 0xffff0000, v2
	v_cmp_ne_u32_e32 vcc, v2, v1
	s_or_b64 s[6:7], vcc, s[6:7]
	s_andn2_b64 exec, exec, s[6:7]
	s_cbranch_execnz .LBB0_14

; __device__ __forceinline__ unsigned xb_ld(unsigned* p)              { return __hip_atomic_load(p, __ATOMIC_RELAXED, __HIP_MEMORY_SCOPE_AGENT); }
; __device__ __forceinline__ void xcd_barrier_complete(unsigned* bar, unsigned x, unsigned& nloc, unsigned& nx) {
;     ...
;     for (;;) {
;         sum = 0u; cnt = 0u; mine = 0u;
; #pragma unroll
;         for (unsigned j = 0; j < 16; ++j) { const unsigned c = xb_ld(&bar[XB_XCNT(j)]); sum += c; cnt += (c > 0u) ? 1u : 0u; mine = (j == x) ? c : mine; }
;         if (sum == G) break;
;         __builtin_amdgcn_s_sleep(1);
;         if ((++sp & 255u) == 0u) { if (xb_ld(&bar[XB_TMO])) break; if (sp > XB_SPIN_CAP) { atomicAdd(&bar[XB_TMO], 1u); break; } }
;     }
.LBB0_131:
	global_load_dword v15, v16, s[8:9] sc1
	s_waitcnt lgkmcnt(0)
	global_load_dword v0, v16, s[12:13] sc1
	global_load_dword v1, v16, s[14:15] sc1
	global_load_dword v2, v16, s[18:19] sc1
	global_load_dword v3, v16, s[22:23] sc1
	global_load_dword v4, v16, s[24:25] sc1
	global_load_dword v5, v16, s[26:27] sc1
	global_load_dword v6, v16, s[34:35] sc1
	global_load_dword v7, v16, s[38:39] sc1
	global_load_dword v8, v16, s[40:41] sc1
	global_load_dword v9, v16, s[42:43] sc1
	global_load_dword v10, v16, s[56:57] sc1
	global_load_dword v11, v16, s[62:63] sc1
	global_load_dword v12, v16, s[64:65] sc1
	global_load_dword v13, v16, s[68:69] sc1
	global_load_dword v14, v16, s[70:71] sc1
	s_mov_b64 s[72:73], -1
	s_mov_b64 s[74:75], -1
	s_waitcnt vmcnt(14)
	v_add_u32_e32 v17, v0, v15
	s_waitcnt vmcnt(13)
	v_add_u32_e32 v17, v17, v1
	s_waitcnt vmcnt(12)
	v_add_u32_e32 v17, v17, v2
	s_waitcnt vmcnt(11)
	v_add_u32_e32 v17, v17, v3
	s_waitcnt vmcnt(10)
	v_add_u32_e32 v17, v17, v4
	s_waitcnt vmcnt(9)
	v_add_u32_e32 v17, v17, v5
	s_waitcnt vmcnt(8)
	v_add_u32_e32 v17, v17, v6
	s_waitcnt vmcnt(7)
	v_add_u32_e32 v17, v17, v7
	s_waitcnt vmcnt(6)
	v_add_u32_e32 v17, v17, v8
	s_waitcnt vmcnt(5)
	v_add_u32_e32 v17, v17, v9
	s_waitcnt vmcnt(4)
	v_add_u32_e32 v17, v17, v10
	s_waitcnt vmcnt(3)
	v_add_u32_e32 v17, v17, v11
	s_waitcnt vmcnt(2)
	v_add_u32_e32 v17, v17, v12
	s_waitcnt vmcnt(1)
	v_add_u32_e32 v17, v17, v13
	s_waitcnt vmcnt(0)
	v_add_u32_e32 v17, v17, v14
	v_cmp_eq_u32_e32 vcc, s3, v17
	s_cbranch_vccnz .LBB0_130
	s_and_b32 s72, s33, 0xff
	s_cmp_eq_u32 s72, 0
	s_mov_b64 s[72:73], -1
	s_mov_b64 s[76:77], -1
	s_cbranch_scc1 .LBB0_135
	s_and_b64 vcc, exec, s[76:77]
	s_cbranch_vccz .LBB0_130

; __device__ __forceinline__ unsigned xb_ld(unsigned* p)              { return __hip_atomic_load(p, __ATOMIC_RELAXED, __HIP_MEMORY_SCOPE_AGENT); }
; __device__ __forceinline__ unsigned xb_add(unsigned* p, unsigned v) { return __hip_atomic_fetch_add(p, v, __ATOMIC_RELAXED, __HIP_MEMORY_SCOPE_AGENT); }
; #define XB_SPIN(cond, bar) do { unsigned _sp = 0; while (cond) { __builtin_amdgcn_s_sleep(1); \
;     if ((++_sp & 255u) == 0u) { if (xb_ld(&(bar)[XB_TMO])) break; if (_sp > XB_SPIN_CAP) { atomicAdd(&(bar)[XB_TMO], 1u); break; } } } } while (0)
; __device__ __forceinline__ void xcd_barrier(const XcdBarrier& b) {
;     ...
;             const unsigned og = xb_add(&bar[XB_TOP], 1u);
;             const unsigned tg = og / nx;
;             if (og + 1u == (tg + 1u) * nx) xb_add(&bar[XB_TOPGEN], 1u);
;             else XB_SPIN(xb_ld(&bar[XB_TOPGEN]) == tg, bar);
;             __builtin_amdgcn_fence(__ATOMIC_ACQUIRE, "agent");
;             xb_add(&bar[XB_XGEN(b.x)], 1u);
;             asm volatile("s_waitcnt vmcnt(0)" ::: "memory");
;         } else {
;             XB_SPIN(xb_ld(&bar[XB_XGEN(b.x)]) == gen, bar);
.LBB0_149:
	s_and_b32 s33, s3, 0xff
	s_mov_b64 s[26:27], -1
	s_cmp_lg_u32 s33, 0
	s_mov_b64 s[38:39], -1
	s_cbranch_scc0 .LBB0_152
	s_and_b64 vcc, exec, s[38:39]
	s_cbranch_vccz .LBB0_148

; __device__ __forceinline__ unsigned xb_ld(unsigned* p)              { return __hip_atomic_load(p, __ATOMIC_RELAXED, __HIP_MEMORY_SCOPE_AGENT); }
; __device__ __forceinline__ unsigned xb_add(unsigned* p, unsigned v) { return __hip_atomic_fetch_add(p, v, __ATOMIC_RELAXED, __HIP_MEMORY_SCOPE_AGENT); }
; #define XB_SPIN(cond, bar) do { unsigned _sp = 0; while (cond) { __builtin_amdgcn_s_sleep(1); \
;     if ((++_sp & 255u) == 0u) { if (xb_ld(&(bar)[XB_TMO])) break; if (_sp > XB_SPIN_CAP) { atomicAdd(&(bar)[XB_TMO], 1u); break; } } } } while (0)
; __device__ __forceinline__ void xcd_barrier(const XcdBarrier& b) {
;     ...
;             const unsigned og = xb_add(&bar[XB_TOP], 1u);
;             const unsigned tg = og / nx;
;             if (og + 1u == (tg + 1u) * nx) xb_add(&bar[XB_TOPGEN], 1u);
;             else XB_SPIN(xb_ld(&bar[XB_TOPGEN]) == tg, bar);
;             __builtin_amdgcn_fence(__ATOMIC_ACQUIRE, "agent");
;             xb_add(&bar[XB_XGEN(b.x)], 1u);
;             asm volatile("s_waitcnt vmcnt(0)" ::: "memory");
;         } else {
;             XB_SPIN(xb_ld(&bar[XB_XGEN(b.x)]) == gen, bar);
.LBB0_166:
	s_and_b32 s26, s3, 0xff
	s_cmp_lg_u32 s26, 0
	s_mov_b64 s[34:35], -1
	s_cbranch_scc0 .LBB0_169
	s_mov_b64 s[38:39], -1
	s_and_b64 vcc, exec, s[34:35]
	s_cbranch_vccz .LBB0_165

; __device__ __forceinline__ unsigned xb_ld(unsigned* p)              { return __hip_atomic_load(p, __ATOMIC_RELAXED, __HIP_MEMORY_SCOPE_AGENT); }
; __device__ __forceinline__ void xcd_barrier_complete(unsigned* bar, unsigned x, unsigned& nloc, unsigned& nx) {
;     ...
;     for (;;) {
;         sum = 0u; cnt = 0u; mine = 0u;
; #pragma unroll
;         for (unsigned j = 0; j < 16; ++j) { const unsigned c = xb_ld(&bar[XB_XCNT(j)]); sum += c; cnt += (c > 0u) ? 1u : 0u; mine = (j == x) ? c : mine; }
;         if (sum == G) break;
;         __builtin_amdgcn_s_sleep(1);
;         if ((++sp & 255u) == 0u) { if (xb_ld(&bar[XB_TMO])) break; if (sp > XB_SPIN_CAP) { atomicAdd(&bar[XB_TMO], 1u); break; } }
;     }
.LBB0_236:
	global_load_dword v15, v16, s[8:9] sc1
	s_waitcnt lgkmcnt(0)
	global_load_dword v0, v16, s[10:11] sc1
	global_load_dword v1, v16, s[12:13] sc1
	global_load_dword v2, v16, s[14:15] sc1
	global_load_dword v3, v16, s[18:19] sc1
	global_load_dword v4, v16, s[22:23] sc1
	global_load_dword v5, v16, s[34:35] sc1
	global_load_dword v6, v16, s[38:39] sc1
	global_load_dword v7, v16, s[40:41] sc1
	global_load_dword v8, v16, s[42:43] sc1
	global_load_dword v9, v16, s[56:57] sc1
	global_load_dword v10, v16, s[62:63] sc1
	global_load_dword v11, v16, s[64:65] sc1
	global_load_dword v12, v16, s[68:69] sc1
	global_load_dword v13, v16, s[70:71] sc1
	global_load_dword v14, v16, s[72:73] sc1
	s_mov_b64 s[74:75], -1
	s_mov_b64 s[76:77], -1
	s_waitcnt vmcnt(14)
	v_add_u32_e32 v17, v0, v15
	s_waitcnt vmcnt(13)
	v_add_u32_e32 v17, v17, v1
	s_waitcnt vmcnt(12)
	v_add_u32_e32 v17, v17, v2
	s_waitcnt vmcnt(11)
	v_add_u32_e32 v17, v17, v3
	s_waitcnt vmcnt(10)
	v_add_u32_e32 v17, v17, v4
	s_waitcnt vmcnt(9)
	v_add_u32_e32 v17, v17, v5
	s_waitcnt vmcnt(8)
	v_add_u32_e32 v17, v17, v6
	s_waitcnt vmcnt(7)
	v_add_u32_e32 v17, v17, v7
	s_waitcnt vmcnt(6)
	v_add_u32_e32 v17, v17, v8
	s_waitcnt vmcnt(5)
	v_add_u32_e32 v17, v17, v9
	s_waitcnt vmcnt(4)
	v_add_u32_e32 v17, v17, v10
	s_waitcnt vmcnt(3)
	v_add_u32_e32 v17, v17, v11
	s_waitcnt vmcnt(2)
	v_add_u32_e32 v17, v17, v12
	s_waitcnt vmcnt(1)
	v_add_u32_e32 v17, v17, v13
	s_waitcnt vmcnt(0)
	v_add_u32_e32 v17, v17, v14
	v_cmp_eq_u32_e32 vcc, s3, v17
	s_cbranch_vccnz .LBB0_235
	s_and_b32 s74, s33, 0xff
	s_cmp_eq_u32 s74, 0
	s_mov_b64 s[74:75], -1
	s_mov_b64 s[78:79], -1
	s_cbranch_scc1 .LBB0_240
	s_and_b64 vcc, exec, s[78:79]
	s_cbranch_vccz .LBB0_235

; __device__ __forceinline__ unsigned xb_ld(unsigned* p)              { return __hip_atomic_load(p, __ATOMIC_RELAXED, __HIP_MEMORY_SCOPE_AGENT); }
; __device__ __forceinline__ unsigned xb_add(unsigned* p, unsigned v) { return __hip_atomic_fetch_add(p, v, __ATOMIC_RELAXED, __HIP_MEMORY_SCOPE_AGENT); }
; #define XB_SPIN(cond, bar) do { unsigned _sp = 0; while (cond) { __builtin_amdgcn_s_sleep(1); \
;     if ((++_sp & 255u) == 0u) { if (xb_ld(&(bar)[XB_TMO])) break; if (_sp > XB_SPIN_CAP) { atomicAdd(&(bar)[XB_TMO], 1u); break; } } } } while (0)
; __device__ __forceinline__ void xcd_barrier(const XcdBarrier& b) {
;     ...
;             const unsigned og = xb_add(&bar[XB_TOP], 1u);
;             const unsigned tg = og / nx;
;             if (og + 1u == (tg + 1u) * nx) xb_add(&bar[XB_TOPGEN], 1u);
;             else XB_SPIN(xb_ld(&bar[XB_TOPGEN]) == tg, bar);
;             __builtin_amdgcn_fence(__ATOMIC_ACQUIRE, "agent");
;             xb_add(&bar[XB_XGEN(b.x)], 1u);
;             asm volatile("s_waitcnt vmcnt(0)" ::: "memory");
;         } else {
;             XB_SPIN(xb_ld(&bar[XB_XGEN(b.x)]) == gen, bar);
.LBB0_254:
	s_and_b32 s33, s3, 0xff
	s_mov_b64 s[34:35], -1
	s_cmp_lg_u32 s33, 0
	s_mov_b64 s[40:41], -1
	s_cbranch_scc0 .LBB0_257
	s_and_b64 vcc, exec, s[40:41]
	s_cbranch_vccz .LBB0_253

; __device__ __forceinline__ unsigned xb_ld(unsigned* p)              { return __hip_atomic_load(p, __ATOMIC_RELAXED, __HIP_MEMORY_SCOPE_AGENT); }
; __device__ __forceinline__ unsigned xb_add(unsigned* p, unsigned v) { return __hip_atomic_fetch_add(p, v, __ATOMIC_RELAXED, __HIP_MEMORY_SCOPE_AGENT); }
; #define XB_SPIN(cond, bar) do { unsigned _sp = 0; while (cond) { __builtin_amdgcn_s_sleep(1); \
;     if ((++_sp & 255u) == 0u) { if (xb_ld(&(bar)[XB_TMO])) break; if (_sp > XB_SPIN_CAP) { atomicAdd(&(bar)[XB_TMO], 1u); break; } } } } while (0)
; __device__ __forceinline__ void xcd_barrier(const XcdBarrier& b) {
;     ...
;             const unsigned og = xb_add(&bar[XB_TOP], 1u);
;             const unsigned tg = og / nx;
;             if (og + 1u == (tg + 1u) * nx) xb_add(&bar[XB_TOPGEN], 1u);
;             else XB_SPIN(xb_ld(&bar[XB_TOPGEN]) == tg, bar);
;             __builtin_amdgcn_fence(__ATOMIC_ACQUIRE, "agent");
;             xb_add(&bar[XB_XGEN(b.x)], 1u);
;             asm volatile("s_waitcnt vmcnt(0)" ::: "memory");
;         } else {
;             XB_SPIN(xb_ld(&bar[XB_XGEN(b.x)]) == gen, bar);
.LBB0_271:
	s_and_b32 s33, s3, 0xff
	s_cmp_lg_u32 s33, 0
	s_mov_b64 s[38:39], -1
	s_cbranch_scc0 .LBB0_274
	s_mov_b64 s[40:41], -1
	s_and_b64 vcc, exec, s[38:39]
	s_cbranch_vccz .LBB0_270

; __device__ __forceinline__ unsigned xb_ld(unsigned* p)              { return __hip_atomic_load(p, __ATOMIC_RELAXED, __HIP_MEMORY_SCOPE_AGENT); }
; __device__ __forceinline__ void xcd_barrier_complete(unsigned* bar, unsigned x, unsigned& nloc, unsigned& nx) {
;     ...
;     for (;;) {
;         sum = 0u; cnt = 0u; mine = 0u;
; #pragma unroll
;         for (unsigned j = 0; j < 16; ++j) { const unsigned c = xb_ld(&bar[XB_XCNT(j)]); sum += c; cnt += (c > 0u) ? 1u : 0u; mine = (j == x) ? c : mine; }
;         if (sum == G) break;
;         __builtin_amdgcn_s_sleep(1);
;         if ((++sp & 255u) == 0u) { if (xb_ld(&bar[XB_TMO])) break; if (sp > XB_SPIN_CAP) { atomicAdd(&bar[XB_TMO], 1u); break; } }
;     }
.LBB0_388:
	global_load_dword v15, v16, s[8:9] sc1
	s_waitcnt lgkmcnt(0)
	global_load_dword v0, v16, s[10:11] sc1
	global_load_dword v1, v16, s[12:13] sc1
	global_load_dword v2, v16, s[14:15] sc1
	global_load_dword v3, v16, s[18:19] sc1
	global_load_dword v4, v16, s[22:23] sc1
	global_load_dword v5, v16, s[28:29] sc1
	global_load_dword v6, v16, s[30:31] sc1
	global_load_dword v7, v16, s[34:35] sc1
	global_load_dword v8, v16, s[38:39] sc1
	global_load_dword v9, v16, s[42:43] sc1
	global_load_dword v10, v16, s[52:53] sc1
	global_load_dword v11, v16, s[54:55] sc1
	global_load_dword v12, v16, s[56:57] sc1
	global_load_dword v13, v16, s[62:63] sc1
	global_load_dword v14, v16, s[64:65] sc1
	s_mov_b64 s[68:69], -1
	s_mov_b64 s[70:71], -1
	s_waitcnt vmcnt(14)
	v_add_u32_e32 v17, v0, v15
	s_waitcnt vmcnt(13)
	v_add_u32_e32 v17, v17, v1
	s_waitcnt vmcnt(12)
	v_add_u32_e32 v17, v17, v2
	s_waitcnt vmcnt(11)
	v_add_u32_e32 v17, v17, v3
	s_waitcnt vmcnt(10)
	v_add_u32_e32 v17, v17, v4
	s_waitcnt vmcnt(9)
	v_add_u32_e32 v17, v17, v5
	s_waitcnt vmcnt(8)
	v_add_u32_e32 v17, v17, v6
	s_waitcnt vmcnt(7)
	v_add_u32_e32 v17, v17, v7
	s_waitcnt vmcnt(6)
	v_add_u32_e32 v17, v17, v8
	s_waitcnt vmcnt(5)
	v_add_u32_e32 v17, v17, v9
	s_waitcnt vmcnt(4)
	v_add_u32_e32 v17, v17, v10
	s_waitcnt vmcnt(3)
	v_add_u32_e32 v17, v17, v11
	s_waitcnt vmcnt(2)
	v_add_u32_e32 v17, v17, v12
	s_waitcnt vmcnt(1)
	v_add_u32_e32 v17, v17, v13
	s_waitcnt vmcnt(0)
	v_add_u32_e32 v17, v17, v14
	v_cmp_eq_u32_e32 vcc, s3, v17
	s_cbranch_vccnz .LBB0_387
	s_and_b32 s68, s33, 0xff
	s_cmp_eq_u32 s68, 0
	s_mov_b64 s[68:69], -1
	s_mov_b64 s[72:73], -1
	s_cbranch_scc1 .LBB0_392
	s_and_b64 vcc, exec, s[72:73]
	s_cbranch_vccz .LBB0_386

; __device__ __forceinline__ unsigned xb_ld(unsigned* p)              { return __hip_atomic_load(p, __ATOMIC_RELAXED, __HIP_MEMORY_SCOPE_AGENT); }
; __device__ __forceinline__ unsigned xb_add(unsigned* p, unsigned v) { return __hip_atomic_fetch_add(p, v, __ATOMIC_RELAXED, __HIP_MEMORY_SCOPE_AGENT); }
; #define XB_SPIN(cond, bar) do { unsigned _sp = 0; while (cond) { __builtin_amdgcn_s_sleep(1); \
;     if ((++_sp & 255u) == 0u) { if (xb_ld(&(bar)[XB_TMO])) break; if (_sp > XB_SPIN_CAP) { atomicAdd(&(bar)[XB_TMO], 1u); break; } } } } while (0)
; __device__ __forceinline__ void xcd_barrier(const XcdBarrier& b) {
;     ...
;             const unsigned og = xb_add(&bar[XB_TOP], 1u);
;             const unsigned tg = og / nx;
;             if (og + 1u == (tg + 1u) * nx) xb_add(&bar[XB_TOPGEN], 1u);
;             else XB_SPIN(xb_ld(&bar[XB_TOPGEN]) == tg, bar);
;             __builtin_amdgcn_fence(__ATOMIC_ACQUIRE, "agent");
;             xb_add(&bar[XB_XGEN(b.x)], 1u);
;             asm volatile("s_waitcnt vmcnt(0)" ::: "memory");
;         } else {
;             XB_SPIN(xb_ld(&bar[XB_XGEN(b.x)]) == gen, bar);
.LBB0_406:
	s_and_b32 s30, s3, 0xff
	s_mov_b64 s[28:29], -1
	s_cmp_lg_u32 s30, 0
	s_mov_b64 s[34:35], -1
	s_cbranch_scc0 .LBB0_409
	s_and_b64 vcc, exec, s[34:35]
	s_cbranch_vccz .LBB0_405

; __device__ __forceinline__ unsigned xb_ld(unsigned* p)              { return __hip_atomic_load(p, __ATOMIC_RELAXED, __HIP_MEMORY_SCOPE_AGENT); }
; __device__ __forceinline__ unsigned xb_add(unsigned* p, unsigned v) { return __hip_atomic_fetch_add(p, v, __ATOMIC_RELAXED, __HIP_MEMORY_SCOPE_AGENT); }
; #define XB_SPIN(cond, bar) do { unsigned _sp = 0; while (cond) { __builtin_amdgcn_s_sleep(1); \
;     if ((++_sp & 255u) == 0u) { if (xb_ld(&(bar)[XB_TMO])) break; if (_sp > XB_SPIN_CAP) { atomicAdd(&(bar)[XB_TMO], 1u); break; } } } } while (0)
; __device__ __forceinline__ void xcd_barrier(const XcdBarrier& b) {
;     ...
;             const unsigned og = xb_add(&bar[XB_TOP], 1u);
;             const unsigned tg = og / nx;
;             if (og + 1u == (tg + 1u) * nx) xb_add(&bar[XB_TOPGEN], 1u);
;             else XB_SPIN(xb_ld(&bar[XB_TOPGEN]) == tg, bar);
;             __builtin_amdgcn_fence(__ATOMIC_ACQUIRE, "agent");
;             xb_add(&bar[XB_XGEN(b.x)], 1u);
;             asm volatile("s_waitcnt vmcnt(0)" ::: "memory");
;         } else {
;             XB_SPIN(xb_ld(&bar[XB_XGEN(b.x)]) == gen, bar);
.LBB0_423:
	s_and_b32 s28, s3, 0xff
	s_cmp_lg_u32 s28, 0
	s_mov_b64 s[30:31], -1
	s_cbranch_scc0 .LBB0_426
	s_mov_b64 s[34:35], -1
	s_and_b64 vcc, exec, s[30:31]
	s_cbranch_vccz .LBB0_422

; __device__ __forceinline__ unsigned xb_ld(unsigned* p)              { return __hip_atomic_load(p, __ATOMIC_RELAXED, __HIP_MEMORY_SCOPE_AGENT); }
; __device__ __forceinline__ void xcd_barrier_complete(unsigned* bar, unsigned x, unsigned& nloc, unsigned& nx) {
;     ...
;     for (;;) {
;         sum = 0u; cnt = 0u; mine = 0u;
; #pragma unroll
;         for (unsigned j = 0; j < 16; ++j) { const unsigned c = xb_ld(&bar[XB_XCNT(j)]); sum += c; cnt += (c > 0u) ? 1u : 0u; mine = (j == x) ? c : mine; }
;         if (sum == G) break;
;         __builtin_amdgcn_s_sleep(1);
;         if ((++sp & 255u) == 0u) { if (xb_ld(&bar[XB_TMO])) break; if (sp > XB_SPIN_CAP) { atomicAdd(&bar[XB_TMO], 1u); break; } }
;     }
.LBB0_485:
	global_load_dword v15, v16, s[8:9] sc1
	s_waitcnt lgkmcnt(0)
	global_load_dword v0, v16, s[10:11] sc1
	global_load_dword v1, v16, s[12:13] sc1
	global_load_dword v2, v16, s[14:15] sc1
	global_load_dword v3, v16, s[16:17] sc1
	global_load_dword v4, v16, s[18:19] sc1
	global_load_dword v5, v16, s[22:23] sc1
	global_load_dword v6, v16, s[28:29] sc1
	global_load_dword v7, v16, s[30:31] sc1
	global_load_dword v8, v16, s[34:35] sc1
	global_load_dword v9, v16, s[38:39] sc1
	global_load_dword v10, v16, s[42:43] sc1
	global_load_dword v11, v16, s[52:53] sc1
	global_load_dword v12, v16, s[54:55] sc1
	global_load_dword v13, v16, s[56:57] sc1
	global_load_dword v14, v16, s[62:63] sc1
	s_mov_b64 s[64:65], -1
	s_mov_b64 s[68:69], -1
	s_waitcnt vmcnt(14)
	v_add_u32_e32 v17, v0, v15
	s_waitcnt vmcnt(13)
	v_add_u32_e32 v17, v17, v1
	s_waitcnt vmcnt(12)
	v_add_u32_e32 v17, v17, v2
	s_waitcnt vmcnt(11)
	v_add_u32_e32 v17, v17, v3
	s_waitcnt vmcnt(10)
	v_add_u32_e32 v17, v17, v4
	s_waitcnt vmcnt(9)
	v_add_u32_e32 v17, v17, v5
	s_waitcnt vmcnt(8)
	v_add_u32_e32 v17, v17, v6
	s_waitcnt vmcnt(7)
	v_add_u32_e32 v17, v17, v7
	s_waitcnt vmcnt(6)
	v_add_u32_e32 v17, v17, v8
	s_waitcnt vmcnt(5)
	v_add_u32_e32 v17, v17, v9
	s_waitcnt vmcnt(4)
	v_add_u32_e32 v17, v17, v10
	s_waitcnt vmcnt(3)
	v_add_u32_e32 v17, v17, v11
	s_waitcnt vmcnt(2)
	v_add_u32_e32 v17, v17, v12
	s_waitcnt vmcnt(1)
	v_add_u32_e32 v17, v17, v13
	s_waitcnt vmcnt(0)
	v_add_u32_e32 v17, v17, v14
	v_cmp_eq_u32_e32 vcc, s3, v17
	s_cbranch_vccnz .LBB0_484
	s_and_b32 s64, s33, 0xff
	s_cmp_eq_u32 s64, 0
	s_mov_b64 s[64:65], -1
	s_mov_b64 s[70:71], -1
	s_cbranch_scc1 .LBB0_489
	s_and_b64 vcc, exec, s[70:71]
	s_cbranch_vccz .LBB0_484

; __device__ __forceinline__ unsigned xb_ld(unsigned* p)              { return __hip_atomic_load(p, __ATOMIC_RELAXED, __HIP_MEMORY_SCOPE_AGENT); }
; __device__ __forceinline__ unsigned xb_add(unsigned* p, unsigned v) { return __hip_atomic_fetch_add(p, v, __ATOMIC_RELAXED, __HIP_MEMORY_SCOPE_AGENT); }
; #define XB_SPIN(cond, bar) do { unsigned _sp = 0; while (cond) { __builtin_amdgcn_s_sleep(1); \
;     if ((++_sp & 255u) == 0u) { if (xb_ld(&(bar)[XB_TMO])) break; if (_sp > XB_SPIN_CAP) { atomicAdd(&(bar)[XB_TMO], 1u); break; } } } } while (0)
; __device__ __forceinline__ void xcd_barrier(const XcdBarrier& b) {
;     ...
;             const unsigned og = xb_add(&bar[XB_TOP], 1u);
;             const unsigned tg = og / nx;
;             if (og + 1u == (tg + 1u) * nx) xb_add(&bar[XB_TOPGEN], 1u);
;             else XB_SPIN(xb_ld(&bar[XB_TOPGEN]) == tg, bar);
;             __builtin_amdgcn_fence(__ATOMIC_ACQUIRE, "agent");
;             xb_add(&bar[XB_XGEN(b.x)], 1u);
;             asm volatile("s_waitcnt vmcnt(0)" ::: "memory");
;         } else {
;             XB_SPIN(xb_ld(&bar[XB_XGEN(b.x)]) == gen, bar);
.LBB0_503:
	s_and_b32 s28, s3, 0xff
	s_mov_b64 s[22:23], -1
	s_cmp_lg_u32 s28, 0
	s_mov_b64 s[30:31], -1
	s_cbranch_scc0 .LBB0_506
	s_and_b64 vcc, exec, s[30:31]
	s_cbranch_vccz .LBB0_502

; __device__ __forceinline__ unsigned xb_ld(unsigned* p)              { return __hip_atomic_load(p, __ATOMIC_RELAXED, __HIP_MEMORY_SCOPE_AGENT); }
; __device__ __forceinline__ unsigned xb_add(unsigned* p, unsigned v) { return __hip_atomic_fetch_add(p, v, __ATOMIC_RELAXED, __HIP_MEMORY_SCOPE_AGENT); }
; #define XB_SPIN(cond, bar) do { unsigned _sp = 0; while (cond) { __builtin_amdgcn_s_sleep(1); \
;     if ((++_sp & 255u) == 0u) { if (xb_ld(&(bar)[XB_TMO])) break; if (_sp > XB_SPIN_CAP) { atomicAdd(&(bar)[XB_TMO], 1u); break; } } } } while (0)
; __device__ __forceinline__ void xcd_barrier(const XcdBarrier& b) {
;     ...
;             const unsigned og = xb_add(&bar[XB_TOP], 1u);
;             const unsigned tg = og / nx;
;             if (og + 1u == (tg + 1u) * nx) xb_add(&bar[XB_TOPGEN], 1u);
;             else XB_SPIN(xb_ld(&bar[XB_TOPGEN]) == tg, bar);
;             __builtin_amdgcn_fence(__ATOMIC_ACQUIRE, "agent");
;             xb_add(&bar[XB_XGEN(b.x)], 1u);
;             asm volatile("s_waitcnt vmcnt(0)" ::: "memory");
;         } else {
;             XB_SPIN(xb_ld(&bar[XB_XGEN(b.x)]) == gen, bar);
.LBB0_520:
	s_and_b32 s22, s3, 0xff
	s_cmp_lg_u32 s22, 0
	s_mov_b64 s[28:29], -1
	s_cbranch_scc0 .LBB0_523
	s_mov_b64 s[30:31], -1
	s_and_b64 vcc, exec, s[28:29]
	s_cbranch_vccz .LBB0_519

; __device__ __forceinline__ unsigned xb_ld(unsigned* p)              { return __hip_atomic_load(p, __ATOMIC_RELAXED, __HIP_MEMORY_SCOPE_AGENT); }
; __device__ __forceinline__ void xcd_barrier_complete(unsigned* bar, unsigned x, unsigned& nloc, unsigned& nx) {
;     ...
;     for (;;) {
;         sum = 0u; cnt = 0u; mine = 0u;
; #pragma unroll
;         for (unsigned j = 0; j < 16; ++j) { const unsigned c = xb_ld(&bar[XB_XCNT(j)]); sum += c; cnt += (c > 0u) ? 1u : 0u; mine = (j == x) ? c : mine; }
;         if (sum == G) break;
;         __builtin_amdgcn_s_sleep(1);
;         if ((++sp & 255u) == 0u) { if (xb_ld(&bar[XB_TMO])) break; if (sp > XB_SPIN_CAP) { atomicAdd(&bar[XB_TMO], 1u); break; } }
;     }
.LBB0_640:
	global_load_dword v15, v16, s[8:9] sc1
	s_waitcnt lgkmcnt(0)
	global_load_dword v0, v16, s[10:11] sc1
	global_load_dword v1, v16, s[12:13] sc1
	global_load_dword v2, v16, s[16:17] sc1
	global_load_dword v3, v16, s[18:19] sc1
	global_load_dword v4, v16, s[22:23] sc1
	global_load_dword v5, v16, s[30:31] sc1
	global_load_dword v6, v16, s[34:35] sc1
	global_load_dword v7, v16, s[38:39] sc1
	global_load_dword v8, v16, s[42:43] sc1
	global_load_dword v9, v16, s[52:53] sc1
	global_load_dword v10, v16, s[54:55] sc1
	global_load_dword v11, v16, s[56:57] sc1
	global_load_dword v12, v16, s[62:63] sc1
	global_load_dword v13, v16, s[64:65] sc1
	global_load_dword v14, v16, s[68:69] sc1
	s_mov_b64 s[70:71], -1
	s_mov_b64 s[72:73], -1
	s_waitcnt vmcnt(14)
	v_add_u32_e32 v17, v0, v15
	s_waitcnt vmcnt(13)
	v_add_u32_e32 v17, v17, v1
	s_waitcnt vmcnt(12)
	v_add_u32_e32 v17, v17, v2
	s_waitcnt vmcnt(11)
	v_add_u32_e32 v17, v17, v3
	s_waitcnt vmcnt(10)
	v_add_u32_e32 v17, v17, v4
	s_waitcnt vmcnt(9)
	v_add_u32_e32 v17, v17, v5
	s_waitcnt vmcnt(8)
	v_add_u32_e32 v17, v17, v6
	s_waitcnt vmcnt(7)
	v_add_u32_e32 v17, v17, v7
	s_waitcnt vmcnt(6)
	v_add_u32_e32 v17, v17, v8
	s_waitcnt vmcnt(5)
	v_add_u32_e32 v17, v17, v9
	s_waitcnt vmcnt(4)
	v_add_u32_e32 v17, v17, v10
	s_waitcnt vmcnt(3)
	v_add_u32_e32 v17, v17, v11
	s_waitcnt vmcnt(2)
	v_add_u32_e32 v17, v17, v12
	s_waitcnt vmcnt(1)
	v_add_u32_e32 v17, v17, v13
	s_waitcnt vmcnt(0)
	v_add_u32_e32 v17, v17, v14
	v_cmp_eq_u32_e32 vcc, s3, v17
	s_cbranch_vccnz .LBB0_639
	s_and_b32 s70, s33, 0xff
	s_cmp_eq_u32 s70, 0
	s_mov_b64 s[70:71], -1
	s_mov_b64 s[74:75], -1
	s_cbranch_scc1 .LBB0_644
	s_and_b64 vcc, exec, s[74:75]
	s_cbranch_vccz .LBB0_639

; __device__ __forceinline__ unsigned xb_ld(unsigned* p)              { return __hip_atomic_load(p, __ATOMIC_RELAXED, __HIP_MEMORY_SCOPE_AGENT); }
; __device__ __forceinline__ unsigned xb_add(unsigned* p, unsigned v) { return __hip_atomic_fetch_add(p, v, __ATOMIC_RELAXED, __HIP_MEMORY_SCOPE_AGENT); }
; #define XB_SPIN(cond, bar) do { unsigned _sp = 0; while (cond) { __builtin_amdgcn_s_sleep(1); \
;     if ((++_sp & 255u) == 0u) { if (xb_ld(&(bar)[XB_TMO])) break; if (_sp > XB_SPIN_CAP) { atomicAdd(&(bar)[XB_TMO], 1u); break; } } } } while (0)
; __device__ __forceinline__ void xcd_barrier(const XcdBarrier& b) {
;     ...
;             const unsigned og = xb_add(&bar[XB_TOP], 1u);
;             const unsigned tg = og / nx;
;             if (og + 1u == (tg + 1u) * nx) xb_add(&bar[XB_TOPGEN], 1u);
;             else XB_SPIN(xb_ld(&bar[XB_TOPGEN]) == tg, bar);
;             __builtin_amdgcn_fence(__ATOMIC_ACQUIRE, "agent");
;             xb_add(&bar[XB_XGEN(b.x)], 1u);
;             asm volatile("s_waitcnt vmcnt(0)" ::: "memory");
;         } else {
;             XB_SPIN(xb_ld(&bar[XB_XGEN(b.x)]) == gen, bar);
.LBB0_658:
	s_and_b32 s33, s3, 0xff
	s_mov_b64 s[30:31], -1
	s_cmp_lg_u32 s33, 0
	s_mov_b64 s[38:39], -1
	s_cbranch_scc0 .LBB0_661
	s_and_b64 vcc, exec, s[38:39]
	s_cbranch_vccz .LBB0_657

; __device__ __forceinline__ unsigned xb_ld(unsigned* p)              { return __hip_atomic_load(p, __ATOMIC_RELAXED, __HIP_MEMORY_SCOPE_AGENT); }
; __device__ __forceinline__ unsigned xb_add(unsigned* p, unsigned v) { return __hip_atomic_fetch_add(p, v, __ATOMIC_RELAXED, __HIP_MEMORY_SCOPE_AGENT); }
; #define XB_SPIN(cond, bar) do { unsigned _sp = 0; while (cond) { __builtin_amdgcn_s_sleep(1); \
;     if ((++_sp & 255u) == 0u) { if (xb_ld(&(bar)[XB_TMO])) break; if (_sp > XB_SPIN_CAP) { atomicAdd(&(bar)[XB_TMO], 1u); break; } } } } while (0)
; __device__ __forceinline__ void xcd_barrier(const XcdBarrier& b) {
;     ...
;             const unsigned og = xb_add(&bar[XB_TOP], 1u);
;             const unsigned tg = og / nx;
;             if (og + 1u == (tg + 1u) * nx) xb_add(&bar[XB_TOPGEN], 1u);
;             else XB_SPIN(xb_ld(&bar[XB_TOPGEN]) == tg, bar);
;             __builtin_amdgcn_fence(__ATOMIC_ACQUIRE, "agent");
;             xb_add(&bar[XB_XGEN(b.x)], 1u);
;             asm volatile("s_waitcnt vmcnt(0)" ::: "memory");
;         } else {
;             XB_SPIN(xb_ld(&bar[XB_XGEN(b.x)]) == gen, bar);
.LBB0_675:
	s_and_b32 s30, s3, 0xff
	s_cmp_lg_u32 s30, 0
	s_mov_b64 s[34:35], -1
	s_cbranch_scc0 .LBB0_678
	s_mov_b64 s[38:39], -1
	s_and_b64 vcc, exec, s[34:35]
	s_cbranch_vccz .LBB0_674

; __device__ __forceinline__ unsigned xb_ld(unsigned* p)              { return __hip_atomic_load(p, __ATOMIC_RELAXED, __HIP_MEMORY_SCOPE_AGENT); }
; __device__ __forceinline__ void xcd_barrier_complete(unsigned* bar, unsigned x, unsigned& nloc, unsigned& nx) {
;     ...
;     for (;;) {
;         sum = 0u; cnt = 0u; mine = 0u;
; #pragma unroll
;         for (unsigned j = 0; j < 16; ++j) { const unsigned c = xb_ld(&bar[XB_XCNT(j)]); sum += c; cnt += (c > 0u) ? 1u : 0u; mine = (j == x) ? c : mine; }
;         if (sum == G) break;
;         __builtin_amdgcn_s_sleep(1);
;         if ((++sp & 255u) == 0u) { if (xb_ld(&bar[XB_TMO])) break; if (sp > XB_SPIN_CAP) { atomicAdd(&bar[XB_TMO], 1u); break; } }
;     }
.LBB0_820:
	global_load_dword v15, v16, s[8:9] sc1
	s_waitcnt lgkmcnt(0)
	global_load_dword v0, v16, s[10:11] sc1
	global_load_dword v1, v16, s[12:13] sc1
	global_load_dword v2, v16, s[16:17] sc1
	global_load_dword v3, v16, s[18:19] sc1
	global_load_dword v4, v16, s[22:23] sc1
	global_load_dword v5, v16, s[34:35] sc1
	global_load_dword v6, v16, s[38:39] sc1
	global_load_dword v7, v16, s[42:43] sc1
	global_load_dword v8, v16, s[52:53] sc1
	global_load_dword v9, v16, s[54:55] sc1
	global_load_dword v10, v16, s[56:57] sc1
	global_load_dword v11, v16, s[62:63] sc1
	global_load_dword v12, v16, s[64:65] sc1
	global_load_dword v13, v16, s[68:69] sc1
	global_load_dword v14, v16, s[70:71] sc1
	s_mov_b64 s[72:73], -1
	s_mov_b64 s[74:75], -1
	s_waitcnt vmcnt(14)
	v_add_u32_e32 v17, v0, v15
	s_waitcnt vmcnt(13)
	v_add_u32_e32 v17, v17, v1
	s_waitcnt vmcnt(12)
	v_add_u32_e32 v17, v17, v2
	s_waitcnt vmcnt(11)
	v_add_u32_e32 v17, v17, v3
	s_waitcnt vmcnt(10)
	v_add_u32_e32 v17, v17, v4
	s_waitcnt vmcnt(9)
	v_add_u32_e32 v17, v17, v5
	s_waitcnt vmcnt(8)
	v_add_u32_e32 v17, v17, v6
	s_waitcnt vmcnt(7)
	v_add_u32_e32 v17, v17, v7
	s_waitcnt vmcnt(6)
	v_add_u32_e32 v17, v17, v8
	s_waitcnt vmcnt(5)
	v_add_u32_e32 v17, v17, v9
	s_waitcnt vmcnt(4)
	v_add_u32_e32 v17, v17, v10
	s_waitcnt vmcnt(3)
	v_add_u32_e32 v17, v17, v11
	s_waitcnt vmcnt(2)
	v_add_u32_e32 v17, v17, v12
	s_waitcnt vmcnt(1)
	v_add_u32_e32 v17, v17, v13
	s_waitcnt vmcnt(0)
	v_add_u32_e32 v17, v17, v14
	v_cmp_eq_u32_e32 vcc, s3, v17
	s_cbranch_vccnz .LBB0_819
	s_and_b32 s72, s33, 0xff
	s_cmp_eq_u32 s72, 0
	s_mov_b64 s[72:73], -1
	s_mov_b64 s[76:77], -1
	s_cbranch_scc1 .LBB0_824
	s_and_b64 vcc, exec, s[76:77]
	s_cbranch_vccz .LBB0_819

; __device__ __forceinline__ unsigned xb_ld(unsigned* p)              { return __hip_atomic_load(p, __ATOMIC_RELAXED, __HIP_MEMORY_SCOPE_AGENT); }
; __device__ __forceinline__ unsigned xb_add(unsigned* p, unsigned v) { return __hip_atomic_fetch_add(p, v, __ATOMIC_RELAXED, __HIP_MEMORY_SCOPE_AGENT); }
; #define XB_SPIN(cond, bar) do { unsigned _sp = 0; while (cond) { __builtin_amdgcn_s_sleep(1); \
;     if ((++_sp & 255u) == 0u) { if (xb_ld(&(bar)[XB_TMO])) break; if (_sp > XB_SPIN_CAP) { atomicAdd(&(bar)[XB_TMO], 1u); break; } } } } while (0)
; __device__ __forceinline__ void xcd_barrier(const XcdBarrier& b) {
;     ...
;             const unsigned og = xb_add(&bar[XB_TOP], 1u);
;             const unsigned tg = og / nx;
;             if (og + 1u == (tg + 1u) * nx) xb_add(&bar[XB_TOPGEN], 1u);
;             else XB_SPIN(xb_ld(&bar[XB_TOPGEN]) == tg, bar);
;             __builtin_amdgcn_fence(__ATOMIC_ACQUIRE, "agent");
;             xb_add(&bar[XB_XGEN(b.x)], 1u);
;             asm volatile("s_waitcnt vmcnt(0)" ::: "memory");
;         } else {
;             XB_SPIN(xb_ld(&bar[XB_XGEN(b.x)]) == gen, bar);
.LBB0_838:
	s_and_b32 s33, s3, 0xff
	s_mov_b64 s[34:35], -1
	s_cmp_lg_u32 s33, 0
	s_mov_b64 s[42:43], -1
	s_cbranch_scc0 .LBB0_841
	s_and_b64 vcc, exec, s[42:43]
	s_cbranch_vccz .LBB0_837

; __device__ __forceinline__ unsigned xb_ld(unsigned* p)              { return __hip_atomic_load(p, __ATOMIC_RELAXED, __HIP_MEMORY_SCOPE_AGENT); }
; __device__ __forceinline__ unsigned xb_add(unsigned* p, unsigned v) { return __hip_atomic_fetch_add(p, v, __ATOMIC_RELAXED, __HIP_MEMORY_SCOPE_AGENT); }
; #define XB_SPIN(cond, bar) do { unsigned _sp = 0; while (cond) { __builtin_amdgcn_s_sleep(1); \
;     if ((++_sp & 255u) == 0u) { if (xb_ld(&(bar)[XB_TMO])) break; if (_sp > XB_SPIN_CAP) { atomicAdd(&(bar)[XB_TMO], 1u); break; } } } } while (0)
; __device__ __forceinline__ void xcd_barrier(const XcdBarrier& b) {
;     ...
;             const unsigned og = xb_add(&bar[XB_TOP], 1u);
;             const unsigned tg = og / nx;
;             if (og + 1u == (tg + 1u) * nx) xb_add(&bar[XB_TOPGEN], 1u);
;             else XB_SPIN(xb_ld(&bar[XB_TOPGEN]) == tg, bar);
;             __builtin_amdgcn_fence(__ATOMIC_ACQUIRE, "agent");
;             xb_add(&bar[XB_XGEN(b.x)], 1u);
;             asm volatile("s_waitcnt vmcnt(0)" ::: "memory");
;         } else {
;             XB_SPIN(xb_ld(&bar[XB_XGEN(b.x)]) == gen, bar);
.LBB0_855:
	s_and_b32 s33, s3, 0xff
	s_cmp_lg_u32 s33, 0
	s_mov_b64 s[38:39], -1
	s_cbranch_scc0 .LBB0_858
	s_mov_b64 s[42:43], -1
	s_and_b64 vcc, exec, s[38:39]
	s_cbranch_vccz .LBB0_854

; __device__ __forceinline__ unsigned xb_ld(unsigned* p)              { return __hip_atomic_load(p, __ATOMIC_RELAXED, __HIP_MEMORY_SCOPE_AGENT); }
; __device__ __forceinline__ void xcd_barrier_complete(unsigned* bar, unsigned x, unsigned& nloc, unsigned& nx) {
;     ...
;     for (;;) {
;         sum = 0u; cnt = 0u; mine = 0u;
; #pragma unroll
;         for (unsigned j = 0; j < 16; ++j) { const unsigned c = xb_ld(&bar[XB_XCNT(j)]); sum += c; cnt += (c > 0u) ? 1u : 0u; mine = (j == x) ? c : mine; }
;         if (sum == G) break;
;         __builtin_amdgcn_s_sleep(1);
;         if ((++sp & 255u) == 0u) { if (xb_ld(&bar[XB_TMO])) break; if (sp > XB_SPIN_CAP) { atomicAdd(&bar[XB_TMO], 1u); break; } }
;     }
.LBB0_949:
	global_load_dword v15, v16, s[8:9] sc1
	s_waitcnt lgkmcnt(0)
	global_load_dword v0, v16, s[10:11] sc1
	global_load_dword v1, v16, s[12:13] sc1
	global_load_dword v2, v16, s[14:15] sc1
	global_load_dword v3, v16, s[16:17] sc1
	global_load_dword v4, v16, s[18:19] sc1
	global_load_dword v5, v16, s[22:23] sc1
	global_load_dword v6, v16, s[34:35] sc1
	global_load_dword v7, v16, s[38:39] sc1
	global_load_dword v8, v16, s[42:43] sc1
	global_load_dword v9, v16, s[52:53] sc1
	global_load_dword v10, v16, s[54:55] sc1
	global_load_dword v11, v16, s[56:57] sc1
	global_load_dword v12, v16, s[62:63] sc1
	global_load_dword v13, v16, s[64:65] sc1
	global_load_dword v14, v16, s[68:69] sc1
	s_mov_b64 s[70:71], -1
	s_mov_b64 s[72:73], -1
	s_waitcnt vmcnt(14)
	v_add_u32_e32 v17, v0, v15
	s_waitcnt vmcnt(13)
	v_add_u32_e32 v17, v17, v1
	s_waitcnt vmcnt(12)
	v_add_u32_e32 v17, v17, v2
	s_waitcnt vmcnt(11)
	v_add_u32_e32 v17, v17, v3
	s_waitcnt vmcnt(10)
	v_add_u32_e32 v17, v17, v4
	s_waitcnt vmcnt(9)
	v_add_u32_e32 v17, v17, v5
	s_waitcnt vmcnt(8)
	v_add_u32_e32 v17, v17, v6
	s_waitcnt vmcnt(7)
	v_add_u32_e32 v17, v17, v7
	s_waitcnt vmcnt(6)
	v_add_u32_e32 v17, v17, v8
	s_waitcnt vmcnt(5)
	v_add_u32_e32 v17, v17, v9
	s_waitcnt vmcnt(4)
	v_add_u32_e32 v17, v17, v10
	s_waitcnt vmcnt(3)
	v_add_u32_e32 v17, v17, v11
	s_waitcnt vmcnt(2)
	v_add_u32_e32 v17, v17, v12
	s_waitcnt vmcnt(1)
	v_add_u32_e32 v17, v17, v13
	s_waitcnt vmcnt(0)
	v_add_u32_e32 v17, v17, v14
	v_cmp_eq_u32_e32 vcc, s3, v17
	s_cbranch_vccnz .LBB0_948
	s_and_b32 s70, s33, 0xff
	s_cmp_eq_u32 s70, 0
	s_mov_b64 s[70:71], -1
	s_mov_b64 s[74:75], -1
	s_cbranch_scc1 .LBB0_953
	s_and_b64 vcc, exec, s[74:75]
	s_cbranch_vccz .LBB0_948

; __device__ __forceinline__ unsigned xb_ld(unsigned* p)              { return __hip_atomic_load(p, __ATOMIC_RELAXED, __HIP_MEMORY_SCOPE_AGENT); }
; __device__ __forceinline__ unsigned xb_add(unsigned* p, unsigned v) { return __hip_atomic_fetch_add(p, v, __ATOMIC_RELAXED, __HIP_MEMORY_SCOPE_AGENT); }
; #define XB_SPIN(cond, bar) do { unsigned _sp = 0; while (cond) { __builtin_amdgcn_s_sleep(1); \
;     if ((++_sp & 255u) == 0u) { if (xb_ld(&(bar)[XB_TMO])) break; if (_sp > XB_SPIN_CAP) { atomicAdd(&(bar)[XB_TMO], 1u); break; } } } } while (0)
; __device__ __forceinline__ void xcd_barrier(const XcdBarrier& b) {
;     ...
;             const unsigned og = xb_add(&bar[XB_TOP], 1u);
;             const unsigned tg = og / nx;
;             if (og + 1u == (tg + 1u) * nx) xb_add(&bar[XB_TOPGEN], 1u);
;             else XB_SPIN(xb_ld(&bar[XB_TOPGEN]) == tg, bar);
;             __builtin_amdgcn_fence(__ATOMIC_ACQUIRE, "agent");
;             xb_add(&bar[XB_XGEN(b.x)], 1u);
;             asm volatile("s_waitcnt vmcnt(0)" ::: "memory");
;         } else {
;             XB_SPIN(xb_ld(&bar[XB_XGEN(b.x)]) == gen, bar);
.LBB0_967:
	s_and_b32 s33, s3, 0xff
	s_mov_b64 s[22:23], -1
	s_cmp_lg_u32 s33, 0
	s_mov_b64 s[38:39], -1
	s_cbranch_scc0 .LBB0_970
	s_and_b64 vcc, exec, s[38:39]
	s_cbranch_vccz .LBB0_966

; __device__ __forceinline__ unsigned xb_ld(unsigned* p)              { return __hip_atomic_load(p, __ATOMIC_RELAXED, __HIP_MEMORY_SCOPE_AGENT); }
; __device__ __forceinline__ unsigned xb_add(unsigned* p, unsigned v) { return __hip_atomic_fetch_add(p, v, __ATOMIC_RELAXED, __HIP_MEMORY_SCOPE_AGENT); }
; #define XB_SPIN(cond, bar) do { unsigned _sp = 0; while (cond) { __builtin_amdgcn_s_sleep(1); \
;     if ((++_sp & 255u) == 0u) { if (xb_ld(&(bar)[XB_TMO])) break; if (_sp > XB_SPIN_CAP) { atomicAdd(&(bar)[XB_TMO], 1u); break; } } } } while (0)
; __device__ __forceinline__ void xcd_barrier(const XcdBarrier& b) {
;     ...
;             const unsigned og = xb_add(&bar[XB_TOP], 1u);
;             const unsigned tg = og / nx;
;             if (og + 1u == (tg + 1u) * nx) xb_add(&bar[XB_TOPGEN], 1u);
;             else XB_SPIN(xb_ld(&bar[XB_TOPGEN]) == tg, bar);
;             __builtin_amdgcn_fence(__ATOMIC_ACQUIRE, "agent");
;             xb_add(&bar[XB_XGEN(b.x)], 1u);
;             asm volatile("s_waitcnt vmcnt(0)" ::: "memory");
;         } else {
;             XB_SPIN(xb_ld(&bar[XB_XGEN(b.x)]) == gen, bar);
.LBB0_984:
	s_and_b32 s22, s3, 0xff
	s_cmp_lg_u32 s22, 0
	s_mov_b64 s[34:35], -1
	s_cbranch_scc0 .LBB0_987
	s_mov_b64 s[38:39], -1
	s_and_b64 vcc, exec, s[34:35]
	s_cbranch_vccz .LBB0_983

; __device__ __forceinline__ unsigned xb_ld(unsigned* p)              { return __hip_atomic_load(p, __ATOMIC_RELAXED, __HIP_MEMORY_SCOPE_AGENT); }
; __device__ __forceinline__ void xcd_barrier_complete(unsigned* bar, unsigned x, unsigned& nloc, unsigned& nx) {
;     ...
;     for (;;) {
;         sum = 0u; cnt = 0u; mine = 0u;
; #pragma unroll
;         for (unsigned j = 0; j < 16; ++j) { const unsigned c = xb_ld(&bar[XB_XCNT(j)]); sum += c; cnt += (c > 0u) ? 1u : 0u; mine = (j == x) ? c : mine; }
;         if (sum == G) break;
;         __builtin_amdgcn_s_sleep(1);
;         if ((++sp & 255u) == 0u) { if (xb_ld(&bar[XB_TMO])) break; if (sp > XB_SPIN_CAP) { atomicAdd(&bar[XB_TMO], 1u); break; } }
;     }
.LBB0_1081:
	global_load_dword v15, v16, s[8:9] sc1
	s_waitcnt lgkmcnt(0)
	global_load_dword v0, v16, s[10:11] sc1
	global_load_dword v1, v16, s[12:13] sc1
	global_load_dword v2, v16, s[14:15] sc1
	global_load_dword v3, v16, s[16:17] sc1
	global_load_dword v4, v16, s[18:19] sc1
	global_load_dword v5, v16, s[20:21] sc1
	global_load_dword v6, v16, s[22:23] sc1
	global_load_dword v7, v16, s[34:35] sc1
	global_load_dword v8, v16, s[38:39] sc1
	global_load_dword v9, v16, s[42:43] sc1
	global_load_dword v10, v16, s[52:53] sc1
	global_load_dword v11, v16, s[54:55] sc1
	global_load_dword v12, v16, s[56:57] sc1
	global_load_dword v13, v16, s[58:59] sc1
	global_load_dword v14, v16, s[62:63] sc1
	s_mov_b64 s[64:65], -1
	s_mov_b64 s[68:69], -1
	s_waitcnt vmcnt(14)
	v_add_u32_e32 v17, v0, v15
	s_waitcnt vmcnt(13)
	v_add_u32_e32 v17, v17, v1
	s_waitcnt vmcnt(12)
	v_add_u32_e32 v17, v17, v2
	s_waitcnt vmcnt(11)
	v_add_u32_e32 v17, v17, v3
	s_waitcnt vmcnt(10)
	v_add_u32_e32 v17, v17, v4
	s_waitcnt vmcnt(9)
	v_add_u32_e32 v17, v17, v5
	s_waitcnt vmcnt(8)
	v_add_u32_e32 v17, v17, v6
	s_waitcnt vmcnt(7)
	v_add_u32_e32 v17, v17, v7
	s_waitcnt vmcnt(6)
	v_add_u32_e32 v17, v17, v8
	s_waitcnt vmcnt(5)
	v_add_u32_e32 v17, v17, v9
	s_waitcnt vmcnt(4)
	v_add_u32_e32 v17, v17, v10
	s_waitcnt vmcnt(3)
	v_add_u32_e32 v17, v17, v11
	s_waitcnt vmcnt(2)
	v_add_u32_e32 v17, v17, v12
	s_waitcnt vmcnt(1)
	v_add_u32_e32 v17, v17, v13
	s_waitcnt vmcnt(0)
	v_add_u32_e32 v17, v17, v14
	v_cmp_eq_u32_e32 vcc, s33, v17
	s_cbranch_vccnz .LBB0_1080
	s_and_b32 s64, s73, 0xff
	s_cmp_eq_u32 s64, 0
	s_mov_b64 s[64:65], -1
	s_mov_b64 s[70:71], -1
	s_cbranch_scc1 .LBB0_1085
	s_and_b64 vcc, exec, s[70:71]
	s_cbranch_vccz .LBB0_1080

; __device__ __forceinline__ unsigned xb_ld(unsigned* p)              { return __hip_atomic_load(p, __ATOMIC_RELAXED, __HIP_MEMORY_SCOPE_AGENT); }
; __device__ __forceinline__ unsigned xb_add(unsigned* p, unsigned v) { return __hip_atomic_fetch_add(p, v, __ATOMIC_RELAXED, __HIP_MEMORY_SCOPE_AGENT); }
; #define XB_SPIN(cond, bar) do { unsigned _sp = 0; while (cond) { __builtin_amdgcn_s_sleep(1); \
;     if ((++_sp & 255u) == 0u) { if (xb_ld(&(bar)[XB_TMO])) break; if (_sp > XB_SPIN_CAP) { atomicAdd(&(bar)[XB_TMO], 1u); break; } } } } while (0)
; __device__ __forceinline__ void xcd_barrier(const XcdBarrier& b) {
;     ...
;             const unsigned og = xb_add(&bar[XB_TOP], 1u);
;             const unsigned tg = og / nx;
;             if (og + 1u == (tg + 1u) * nx) xb_add(&bar[XB_TOPGEN], 1u);
;             else XB_SPIN(xb_ld(&bar[XB_TOPGEN]) == tg, bar);
;             __builtin_amdgcn_fence(__ATOMIC_ACQUIRE, "agent");
;             xb_add(&bar[XB_XGEN(b.x)], 1u);
;             asm volatile("s_waitcnt vmcnt(0)" ::: "memory");
;         } else {
;             XB_SPIN(xb_ld(&bar[XB_XGEN(b.x)]) == gen, bar);
.LBB0_1099:
	s_and_b32 s22, s33, 0xff
	s_mov_b64 s[20:21], -1
	s_cmp_lg_u32 s22, 0
	s_mov_b64 s[34:35], -1
	s_cbranch_scc0 .LBB0_1102
	s_and_b64 vcc, exec, s[34:35]
	s_cbranch_vccz .LBB0_1098

; __device__ __forceinline__ unsigned xb_ld(unsigned* p)              { return __hip_atomic_load(p, __ATOMIC_RELAXED, __HIP_MEMORY_SCOPE_AGENT); }
; __device__ __forceinline__ unsigned xb_add(unsigned* p, unsigned v) { return __hip_atomic_fetch_add(p, v, __ATOMIC_RELAXED, __HIP_MEMORY_SCOPE_AGENT); }
; #define XB_SPIN(cond, bar) do { unsigned _sp = 0; while (cond) { __builtin_amdgcn_s_sleep(1); \
;     if ((++_sp & 255u) == 0u) { if (xb_ld(&(bar)[XB_TMO])) break; if (_sp > XB_SPIN_CAP) { atomicAdd(&(bar)[XB_TMO], 1u); break; } } } } while (0)
; __device__ __forceinline__ void xcd_barrier(const XcdBarrier& b) {
;     ...
;             const unsigned og = xb_add(&bar[XB_TOP], 1u);
;             const unsigned tg = og / nx;
;             if (og + 1u == (tg + 1u) * nx) xb_add(&bar[XB_TOPGEN], 1u);
;             else XB_SPIN(xb_ld(&bar[XB_TOPGEN]) == tg, bar);
;             __builtin_amdgcn_fence(__ATOMIC_ACQUIRE, "agent");
;             xb_add(&bar[XB_XGEN(b.x)], 1u);
;             asm volatile("s_waitcnt vmcnt(0)" ::: "memory");
;         } else {
;             XB_SPIN(xb_ld(&bar[XB_XGEN(b.x)]) == gen, bar);
.LBB0_1116:
	s_and_b32 s20, s33, 0xff
	s_cmp_lg_u32 s20, 0
	s_mov_b64 s[22:23], -1
	s_cbranch_scc0 .LBB0_1119
	s_mov_b64 s[34:35], -1
	s_and_b64 vcc, exec, s[22:23]
	s_cbranch_vccz .LBB0_1115

; __device__ __forceinline__ unsigned xb_ld(unsigned* p)              { return __hip_atomic_load(p, __ATOMIC_RELAXED, __HIP_MEMORY_SCOPE_AGENT); }
; __device__ __forceinline__ void xcd_barrier_complete(unsigned* bar, unsigned x, unsigned& nloc, unsigned& nx) {
;     ...
;     for (;;) {
;         sum = 0u; cnt = 0u; mine = 0u;
; #pragma unroll
;         for (unsigned j = 0; j < 16; ++j) { const unsigned c = xb_ld(&bar[XB_XCNT(j)]); sum += c; cnt += (c > 0u) ? 1u : 0u; mine = (j == x) ? c : mine; }
;         if (sum == G) break;
;         __builtin_amdgcn_s_sleep(1);
;         if ((++sp & 255u) == 0u) { if (xb_ld(&bar[XB_TMO])) break; if (sp > XB_SPIN_CAP) { atomicAdd(&bar[XB_TMO], 1u); break; } }
;     }
.LBB0_1166:
	global_load_dword v15, v16, s[10:11] sc1
	s_waitcnt lgkmcnt(0)
	global_load_dword v0, v16, s[12:13] sc1
	global_load_dword v1, v16, s[14:15] sc1
	global_load_dword v2, v16, s[16:17] sc1
	global_load_dword v3, v16, s[18:19] sc1
	global_load_dword v4, v16, s[20:21] sc1
	global_load_dword v5, v16, s[22:23] sc1
	global_load_dword v6, v16, s[34:35] sc1
	global_load_dword v7, v16, s[38:39] sc1
	global_load_dword v8, v16, s[42:43] sc1
	global_load_dword v9, v16, s[52:53] sc1
	global_load_dword v10, v16, s[54:55] sc1
	global_load_dword v11, v16, s[56:57] sc1
	global_load_dword v12, v16, s[58:59] sc1
	global_load_dword v13, v16, s[62:63] sc1
	global_load_dword v14, v16, s[64:65] sc1
	s_mov_b64 s[68:69], -1
	s_mov_b64 s[70:71], -1
	s_waitcnt vmcnt(14)
	v_add_u32_e32 v17, v0, v15
	s_waitcnt vmcnt(13)
	v_add_u32_e32 v17, v17, v1
	s_waitcnt vmcnt(12)
	v_add_u32_e32 v17, v17, v2
	s_waitcnt vmcnt(11)
	v_add_u32_e32 v17, v17, v3
	s_waitcnt vmcnt(10)
	v_add_u32_e32 v17, v17, v4
	s_waitcnt vmcnt(9)
	v_add_u32_e32 v17, v17, v5
	s_waitcnt vmcnt(8)
	v_add_u32_e32 v17, v17, v6
	s_waitcnt vmcnt(7)
	v_add_u32_e32 v17, v17, v7
	s_waitcnt vmcnt(6)
	v_add_u32_e32 v17, v17, v8
	s_waitcnt vmcnt(5)
	v_add_u32_e32 v17, v17, v9
	s_waitcnt vmcnt(4)
	v_add_u32_e32 v17, v17, v10
	s_waitcnt vmcnt(3)
	v_add_u32_e32 v17, v17, v11
	s_waitcnt vmcnt(2)
	v_add_u32_e32 v17, v17, v12
	s_waitcnt vmcnt(1)
	v_add_u32_e32 v17, v17, v13
	s_waitcnt vmcnt(0)
	v_add_u32_e32 v17, v17, v14
	v_cmp_eq_u32_e32 vcc, s3, v17
	s_cbranch_vccnz .LBB0_1165
	s_and_b32 s68, s33, 0xff
	s_cmp_eq_u32 s68, 0
	s_mov_b64 s[68:69], -1
	s_mov_b64 s[72:73], -1
	s_cbranch_scc1 .LBB0_1170
	s_and_b64 vcc, exec, s[72:73]
	s_cbranch_vccz .LBB0_1164

; __device__ __forceinline__ unsigned xb_ld(unsigned* p)              { return __hip_atomic_load(p, __ATOMIC_RELAXED, __HIP_MEMORY_SCOPE_AGENT); }
; __device__ __forceinline__ void xcd_barrier_complete(unsigned* bar, unsigned x, unsigned& nloc, unsigned& nx) {
;     ...
;     for (;;) {
;         sum = 0u; cnt = 0u; mine = 0u;
; #pragma unroll
;         for (unsigned j = 0; j < 16; ++j) { const unsigned c = xb_ld(&bar[XB_XCNT(j)]); sum += c; cnt += (c > 0u) ? 1u : 0u; mine = (j == x) ? c : mine; }
;         if (sum == G) break;
;         __builtin_amdgcn_s_sleep(1);
;         if ((++sp & 255u) == 0u) { if (xb_ld(&bar[XB_TMO])) break; if (sp > XB_SPIN_CAP) { atomicAdd(&bar[XB_TMO], 1u); break; } }
;     }
.LBB0_1245:
	global_load_dword v15, v16, s[8:9] sc1
	s_waitcnt lgkmcnt(0)
	global_load_dword v0, v16, s[10:11] sc1
	global_load_dword v1, v16, s[12:13] sc1
	global_load_dword v2, v16, s[14:15] sc1
	global_load_dword v3, v16, s[16:17] sc1
	global_load_dword v4, v16, s[18:19] sc1
	global_load_dword v5, v16, s[20:21] sc1
	global_load_dword v6, v16, s[22:23] sc1
	global_load_dword v7, v16, s[34:35] sc1
	global_load_dword v8, v16, s[38:39] sc1
	global_load_dword v9, v16, s[42:43] sc1
	global_load_dword v10, v16, s[52:53] sc1
	global_load_dword v11, v16, s[54:55] sc1
	global_load_dword v12, v16, s[56:57] sc1
	global_load_dword v13, v16, s[58:59] sc1
	global_load_dword v14, v16, s[60:61] sc1
	s_mov_b64 s[62:63], -1
	s_mov_b64 s[64:65], -1
	s_waitcnt vmcnt(14)
	v_add_u32_e32 v17, v0, v15
	s_waitcnt vmcnt(13)
	v_add_u32_e32 v17, v17, v1
	s_waitcnt vmcnt(12)
	v_add_u32_e32 v17, v17, v2
	s_waitcnt vmcnt(11)
	v_add_u32_e32 v17, v17, v3
	s_waitcnt vmcnt(10)
	v_add_u32_e32 v17, v17, v4
	s_waitcnt vmcnt(9)
	v_add_u32_e32 v17, v17, v5
	s_waitcnt vmcnt(8)
	v_add_u32_e32 v17, v17, v6
	s_waitcnt vmcnt(7)
	v_add_u32_e32 v17, v17, v7
	s_waitcnt vmcnt(6)
	v_add_u32_e32 v17, v17, v8
	s_waitcnt vmcnt(5)
	v_add_u32_e32 v17, v17, v9
	s_waitcnt vmcnt(4)
	v_add_u32_e32 v17, v17, v10
	s_waitcnt vmcnt(3)
	v_add_u32_e32 v17, v17, v11
	s_waitcnt vmcnt(2)
	v_add_u32_e32 v17, v17, v12
	s_waitcnt vmcnt(1)
	v_add_u32_e32 v17, v17, v13
	s_waitcnt vmcnt(0)
	v_add_u32_e32 v17, v17, v14
	v_cmp_eq_u32_e32 vcc, s3, v17
	s_cbranch_vccnz .LBB0_1244
	s_and_b32 s62, s33, 0xff
	s_cmp_eq_u32 s62, 0
	s_mov_b64 s[62:63], -1
	s_mov_b64 s[68:69], -1
	s_cbranch_scc1 .LBB0_1249
	s_and_b64 vcc, exec, s[68:69]
	s_cbranch_vccz .LBB0_1244

; __device__ __forceinline__ unsigned xb_ld(unsigned* p)              { return __hip_atomic_load(p, __ATOMIC_RELAXED, __HIP_MEMORY_SCOPE_AGENT); }
; __device__ __forceinline__ unsigned xb_add(unsigned* p, unsigned v) { return __hip_atomic_fetch_add(p, v, __ATOMIC_RELAXED, __HIP_MEMORY_SCOPE_AGENT); }
; #define XB_SPIN(cond, bar) do { unsigned _sp = 0; while (cond) { __builtin_amdgcn_s_sleep(1); \
;     if ((++_sp & 255u) == 0u) { if (xb_ld(&(bar)[XB_TMO])) break; if (_sp > XB_SPIN_CAP) { atomicAdd(&(bar)[XB_TMO], 1u); break; } } } } while (0)
; __device__ __forceinline__ void xcd_barrier(const XcdBarrier& b) {
;     ...
;             const unsigned og = xb_add(&bar[XB_TOP], 1u);
;             const unsigned tg = og / nx;
;             if (og + 1u == (tg + 1u) * nx) xb_add(&bar[XB_TOPGEN], 1u);
;             else XB_SPIN(xb_ld(&bar[XB_TOPGEN]) == tg, bar);
;             __builtin_amdgcn_fence(__ATOMIC_ACQUIRE, "agent");
;             xb_add(&bar[XB_XGEN(b.x)], 1u);
;             asm volatile("s_waitcnt vmcnt(0)" ::: "memory");
;         } else {
;             XB_SPIN(xb_ld(&bar[XB_XGEN(b.x)]) == gen, bar);
.LBB0_1263:
	s_and_b32 s22, s3, 0xff
	s_mov_b64 s[20:21], -1
	s_cmp_lg_u32 s22, 0
	s_mov_b64 s[34:35], -1
	s_cbranch_scc0 .LBB0_1266
	s_and_b64 vcc, exec, s[34:35]
	s_cbranch_vccz .LBB0_1262

; __device__ __forceinline__ unsigned xb_ld(unsigned* p)              { return __hip_atomic_load(p, __ATOMIC_RELAXED, __HIP_MEMORY_SCOPE_AGENT); }
; __device__ __forceinline__ unsigned xb_add(unsigned* p, unsigned v) { return __hip_atomic_fetch_add(p, v, __ATOMIC_RELAXED, __HIP_MEMORY_SCOPE_AGENT); }
; #define XB_SPIN(cond, bar) do { unsigned _sp = 0; while (cond) { __builtin_amdgcn_s_sleep(1); \
;     if ((++_sp & 255u) == 0u) { if (xb_ld(&(bar)[XB_TMO])) break; if (_sp > XB_SPIN_CAP) { atomicAdd(&(bar)[XB_TMO], 1u); break; } } } } while (0)
; __device__ __forceinline__ void xcd_barrier(const XcdBarrier& b) {
;     ...
;             const unsigned og = xb_add(&bar[XB_TOP], 1u);
;             const unsigned tg = og / nx;
;             if (og + 1u == (tg + 1u) * nx) xb_add(&bar[XB_TOPGEN], 1u);
;             else XB_SPIN(xb_ld(&bar[XB_TOPGEN]) == tg, bar);
;             __builtin_amdgcn_fence(__ATOMIC_ACQUIRE, "agent");
;             xb_add(&bar[XB_XGEN(b.x)], 1u);
;             asm volatile("s_waitcnt vmcnt(0)" ::: "memory");
;         } else {
;             XB_SPIN(xb_ld(&bar[XB_XGEN(b.x)]) == gen, bar);
.LBB0_1280:
	s_and_b32 s20, s3, 0xff
	s_cmp_lg_u32 s20, 0
	s_mov_b64 s[22:23], -1
	s_cbranch_scc0 .LBB0_1283
	s_mov_b64 s[34:35], -1
	s_and_b64 vcc, exec, s[22:23]
	s_cbranch_vccz .LBB0_1279

; __device__ __forceinline__ unsigned xb_ld(unsigned* p)              { return __hip_atomic_load(p, __ATOMIC_RELAXED, __HIP_MEMORY_SCOPE_AGENT); }
; __device__ __forceinline__ void xcd_barrier_complete(unsigned* bar, unsigned x, unsigned& nloc, unsigned& nx) {
;     ...
;     for (;;) {
;         sum = 0u; cnt = 0u; mine = 0u;
; #pragma unroll
;         for (unsigned j = 0; j < 16; ++j) { const unsigned c = xb_ld(&bar[XB_XCNT(j)]); sum += c; cnt += (c > 0u) ? 1u : 0u; mine = (j == x) ? c : mine; }
;         if (sum == G) break;
;         __builtin_amdgcn_s_sleep(1);
;         if ((++sp & 255u) == 0u) { if (xb_ld(&bar[XB_TMO])) break; if (sp > XB_SPIN_CAP) { atomicAdd(&bar[XB_TMO], 1u); break; } }
;     }
.LBB0_1576:
	global_load_dword v15, v16, s[8:9] sc1
	s_waitcnt lgkmcnt(0)
	global_load_dword v0, v16, s[10:11] sc1
	global_load_dword v1, v16, s[12:13] sc1
	global_load_dword v2, v16, s[14:15] sc1
	global_load_dword v3, v16, s[16:17] sc1
	global_load_dword v4, v16, s[18:19] sc1
	global_load_dword v5, v16, s[20:21] sc1
	global_load_dword v6, v16, s[22:23] sc1
	global_load_dword v7, v16, s[28:29] sc1
	global_load_dword v8, v16, s[34:35] sc1
	global_load_dword v9, v16, s[36:37] sc1
	global_load_dword v10, v16, s[38:39] sc1
	global_load_dword v11, v16, s[42:43] sc1
	global_load_dword v12, v16, s[52:53] sc1
	global_load_dword v13, v16, s[54:55] sc1
	global_load_dword v14, v16, s[56:57] sc1
	s_mov_b64 s[58:59], -1
	s_mov_b64 s[60:61], -1
	s_waitcnt vmcnt(14)
	v_add_u32_e32 v17, v0, v15
	s_waitcnt vmcnt(13)
	v_add_u32_e32 v17, v17, v1
	s_waitcnt vmcnt(12)
	v_add_u32_e32 v17, v17, v2
	s_waitcnt vmcnt(11)
	v_add_u32_e32 v17, v17, v3
	s_waitcnt vmcnt(10)
	v_add_u32_e32 v17, v17, v4
	s_waitcnt vmcnt(9)
	v_add_u32_e32 v17, v17, v5
	s_waitcnt vmcnt(8)
	v_add_u32_e32 v17, v17, v6
	s_waitcnt vmcnt(7)
	v_add_u32_e32 v17, v17, v7
	s_waitcnt vmcnt(6)
	v_add_u32_e32 v17, v17, v8
	s_waitcnt vmcnt(5)
	v_add_u32_e32 v17, v17, v9
	s_waitcnt vmcnt(4)
	v_add_u32_e32 v17, v17, v10
	s_waitcnt vmcnt(3)
	v_add_u32_e32 v17, v17, v11
	s_waitcnt vmcnt(2)
	v_add_u32_e32 v17, v17, v12
	s_waitcnt vmcnt(1)
	v_add_u32_e32 v17, v17, v13
	s_waitcnt vmcnt(0)
	v_add_u32_e32 v17, v17, v14
	v_cmp_eq_u32_e32 vcc, s3, v17
	s_cbranch_vccnz .LBB0_1575
	s_and_b32 s58, s33, 0xff
	s_cmp_eq_u32 s58, 0
	s_mov_b64 s[58:59], -1
	s_mov_b64 s[62:63], -1
	s_cbranch_scc1 .LBB0_1580
	s_and_b64 vcc, exec, s[62:63]
	s_cbranch_vccz .LBB0_1575

; __device__ __forceinline__ unsigned xb_ld(unsigned* p)              { return __hip_atomic_load(p, __ATOMIC_RELAXED, __HIP_MEMORY_SCOPE_AGENT); }
; __device__ __forceinline__ unsigned xb_add(unsigned* p, unsigned v) { return __hip_atomic_fetch_add(p, v, __ATOMIC_RELAXED, __HIP_MEMORY_SCOPE_AGENT); }
; #define XB_SPIN(cond, bar) do { unsigned _sp = 0; while (cond) { __builtin_amdgcn_s_sleep(1); \
;     if ((++_sp & 255u) == 0u) { if (xb_ld(&(bar)[XB_TMO])) break; if (_sp > XB_SPIN_CAP) { atomicAdd(&(bar)[XB_TMO], 1u); break; } } } } while (0)
; __device__ __forceinline__ void xcd_barrier(const XcdBarrier& b) {
;     ...
;             const unsigned og = xb_add(&bar[XB_TOP], 1u);
;             const unsigned tg = og / nx;
;             if (og + 1u == (tg + 1u) * nx) xb_add(&bar[XB_TOPGEN], 1u);
;             else XB_SPIN(xb_ld(&bar[XB_TOPGEN]) == tg, bar);
;             __builtin_amdgcn_fence(__ATOMIC_ACQUIRE, "agent");
;             xb_add(&bar[XB_XGEN(b.x)], 1u);
;             asm volatile("s_waitcnt vmcnt(0)" ::: "memory");
;         } else {
;             XB_SPIN(xb_ld(&bar[XB_XGEN(b.x)]) == gen, bar);
.LBB0_1594:
	s_and_b32 s22, s3, 0xff
	s_mov_b64 s[20:21], -1
	s_cmp_lg_u32 s22, 0
	s_mov_b64 s[28:29], -1
	s_cbranch_scc0 .LBB0_1597
	s_and_b64 vcc, exec, s[28:29]
	s_cbranch_vccz .LBB0_1593

; __device__ __forceinline__ unsigned xb_ld(unsigned* p)              { return __hip_atomic_load(p, __ATOMIC_RELAXED, __HIP_MEMORY_SCOPE_AGENT); }
; __device__ __forceinline__ unsigned xb_add(unsigned* p, unsigned v) { return __hip_atomic_fetch_add(p, v, __ATOMIC_RELAXED, __HIP_MEMORY_SCOPE_AGENT); }
; #define XB_SPIN(cond, bar) do { unsigned _sp = 0; while (cond) { __builtin_amdgcn_s_sleep(1); \
;     if ((++_sp & 255u) == 0u) { if (xb_ld(&(bar)[XB_TMO])) break; if (_sp > XB_SPIN_CAP) { atomicAdd(&(bar)[XB_TMO], 1u); break; } } } } while (0)
; __device__ __forceinline__ void xcd_barrier(const XcdBarrier& b) {
;     ...
;             const unsigned og = xb_add(&bar[XB_TOP], 1u);
;             const unsigned tg = og / nx;
;             if (og + 1u == (tg + 1u) * nx) xb_add(&bar[XB_TOPGEN], 1u);
;             else XB_SPIN(xb_ld(&bar[XB_TOPGEN]) == tg, bar);
;             __builtin_amdgcn_fence(__ATOMIC_ACQUIRE, "agent");
;             xb_add(&bar[XB_XGEN(b.x)], 1u);
;             asm volatile("s_waitcnt vmcnt(0)" ::: "memory");
;         } else {
;             XB_SPIN(xb_ld(&bar[XB_XGEN(b.x)]) == gen, bar);
.LBB0_1611:
	s_and_b32 s20, s3, 0xff
	s_cmp_lg_u32 s20, 0
	s_mov_b64 s[22:23], -1
	s_cbranch_scc0 .LBB0_1614
	s_mov_b64 s[28:29], -1
	s_and_b64 vcc, exec, s[22:23]
	s_cbranch_vccz .LBB0_1610

; __device__ __forceinline__ unsigned xb_ld(unsigned* p)              { return __hip_atomic_load(p, __ATOMIC_RELAXED, __HIP_MEMORY_SCOPE_AGENT); }
; __device__ __forceinline__ void xcd_barrier_complete(unsigned* bar, unsigned x, unsigned& nloc, unsigned& nx) {
;     ...
;     for (;;) {
;         sum = 0u; cnt = 0u; mine = 0u;
; #pragma unroll
;         for (unsigned j = 0; j < 16; ++j) { const unsigned c = xb_ld(&bar[XB_XCNT(j)]); sum += c; cnt += (c > 0u) ? 1u : 0u; mine = (j == x) ? c : mine; }
;         if (sum == G) break;
;         __builtin_amdgcn_s_sleep(1);
;         if ((++sp & 255u) == 0u) { if (xb_ld(&bar[XB_TMO])) break; if (sp > XB_SPIN_CAP) { atomicAdd(&bar[XB_TMO], 1u); break; } }
;     }
.LBB0_1677:
	global_load_dword v15, v16, s[8:9] sc1
	s_waitcnt lgkmcnt(0)
	global_load_dword v0, v16, s[10:11] sc1
	global_load_dword v1, v16, s[12:13] sc1
	global_load_dword v2, v16, s[14:15] sc1
	global_load_dword v3, v16, s[16:17] sc1
	global_load_dword v4, v16, s[18:19] sc1
	global_load_dword v5, v16, s[20:21] sc1
	global_load_dword v6, v16, s[22:23] sc1
	global_load_dword v7, v16, s[26:27] sc1
	global_load_dword v8, v16, s[28:29] sc1
	global_load_dword v9, v16, s[34:35] sc1
	global_load_dword v10, v16, s[36:37] sc1
	global_load_dword v11, v16, s[38:39] sc1
	global_load_dword v12, v16, s[42:43] sc1
	global_load_dword v13, v16, s[52:53] sc1
	global_load_dword v14, v16, s[54:55] sc1
	s_mov_b64 s[56:57], -1
	s_mov_b64 s[58:59], -1
	s_waitcnt vmcnt(14)
	v_add_u32_e32 v17, v0, v15
	s_waitcnt vmcnt(13)
	v_add_u32_e32 v17, v17, v1
	s_waitcnt vmcnt(12)
	v_add_u32_e32 v17, v17, v2
	s_waitcnt vmcnt(11)
	v_add_u32_e32 v17, v17, v3
	s_waitcnt vmcnt(10)
	v_add_u32_e32 v17, v17, v4
	s_waitcnt vmcnt(9)
	v_add_u32_e32 v17, v17, v5
	s_waitcnt vmcnt(8)
	v_add_u32_e32 v17, v17, v6
	s_waitcnt vmcnt(7)
	v_add_u32_e32 v17, v17, v7
	s_waitcnt vmcnt(6)
	v_add_u32_e32 v17, v17, v8
	s_waitcnt vmcnt(5)
	v_add_u32_e32 v17, v17, v9
	s_waitcnt vmcnt(4)
	v_add_u32_e32 v17, v17, v10
	s_waitcnt vmcnt(3)
	v_add_u32_e32 v17, v17, v11
	s_waitcnt vmcnt(2)
	v_add_u32_e32 v17, v17, v12
	s_waitcnt vmcnt(1)
	v_add_u32_e32 v17, v17, v13
	s_waitcnt vmcnt(0)
	v_add_u32_e32 v17, v17, v14
	v_cmp_eq_u32_e32 vcc, s3, v17
	s_cbranch_vccnz .LBB0_1676
	s_and_b32 s56, s33, 0xff
	s_cmp_eq_u32 s56, 0
	s_mov_b64 s[56:57], -1
	s_mov_b64 s[60:61], -1
	s_cbranch_scc1 .LBB0_1681
	s_and_b64 vcc, exec, s[60:61]
	s_cbranch_vccz .LBB0_1676

; __device__ __forceinline__ unsigned xb_ld(unsigned* p)              { return __hip_atomic_load(p, __ATOMIC_RELAXED, __HIP_MEMORY_SCOPE_AGENT); }
; __device__ __forceinline__ unsigned xb_add(unsigned* p, unsigned v) { return __hip_atomic_fetch_add(p, v, __ATOMIC_RELAXED, __HIP_MEMORY_SCOPE_AGENT); }
; #define XB_SPIN(cond, bar) do { unsigned _sp = 0; while (cond) { __builtin_amdgcn_s_sleep(1); \
;     if ((++_sp & 255u) == 0u) { if (xb_ld(&(bar)[XB_TMO])) break; if (_sp > XB_SPIN_CAP) { atomicAdd(&(bar)[XB_TMO], 1u); break; } } } } while (0)
; __device__ __forceinline__ void xcd_barrier(const XcdBarrier& b) {
;     ...
;             const unsigned og = xb_add(&bar[XB_TOP], 1u);
;             const unsigned tg = og / nx;
;             if (og + 1u == (tg + 1u) * nx) xb_add(&bar[XB_TOPGEN], 1u);
;             else XB_SPIN(xb_ld(&bar[XB_TOPGEN]) == tg, bar);
;             __builtin_amdgcn_fence(__ATOMIC_ACQUIRE, "agent");
;             xb_add(&bar[XB_XGEN(b.x)], 1u);
;             asm volatile("s_waitcnt vmcnt(0)" ::: "memory");
;         } else {
;             XB_SPIN(xb_ld(&bar[XB_XGEN(b.x)]) == gen, bar);
.LBB0_1695:
	s_and_b32 s22, s3, 0xff
	s_mov_b64 s[20:21], -1
	s_cmp_lg_u32 s22, 0
	s_mov_b64 s[26:27], -1
	s_cbranch_scc0 .LBB0_1698
	s_and_b64 vcc, exec, s[26:27]
	s_cbranch_vccz .LBB0_1694

; __device__ __forceinline__ unsigned xb_ld(unsigned* p)              { return __hip_atomic_load(p, __ATOMIC_RELAXED, __HIP_MEMORY_SCOPE_AGENT); }
; __device__ __forceinline__ unsigned xb_add(unsigned* p, unsigned v) { return __hip_atomic_fetch_add(p, v, __ATOMIC_RELAXED, __HIP_MEMORY_SCOPE_AGENT); }
; #define XB_SPIN(cond, bar) do { unsigned _sp = 0; while (cond) { __builtin_amdgcn_s_sleep(1); \
;     if ((++_sp & 255u) == 0u) { if (xb_ld(&(bar)[XB_TMO])) break; if (_sp > XB_SPIN_CAP) { atomicAdd(&(bar)[XB_TMO], 1u); break; } } } } while (0)
; __device__ __forceinline__ void xcd_barrier(const XcdBarrier& b) {
;     ...
;             const unsigned og = xb_add(&bar[XB_TOP], 1u);
;             const unsigned tg = og / nx;
;             if (og + 1u == (tg + 1u) * nx) xb_add(&bar[XB_TOPGEN], 1u);
;             else XB_SPIN(xb_ld(&bar[XB_TOPGEN]) == tg, bar);
;             __builtin_amdgcn_fence(__ATOMIC_ACQUIRE, "agent");
;             xb_add(&bar[XB_XGEN(b.x)], 1u);
;             asm volatile("s_waitcnt vmcnt(0)" ::: "memory");
;         } else {
;             XB_SPIN(xb_ld(&bar[XB_XGEN(b.x)]) == gen, bar);
.LBB0_1712:
	s_and_b32 s20, s3, 0xff
	s_cmp_lg_u32 s20, 0
	s_mov_b64 s[22:23], -1
	s_cbranch_scc0 .LBB0_1715
	s_mov_b64 s[26:27], -1
	s_and_b64 vcc, exec, s[22:23]
	s_cbranch_vccz .LBB0_1711

; __device__ __forceinline__ unsigned xb_ld(unsigned* p)              { return __hip_atomic_load(p, __ATOMIC_RELAXED, __HIP_MEMORY_SCOPE_AGENT); }
; __device__ __forceinline__ void xcd_barrier_complete(unsigned* bar, unsigned x, unsigned& nloc, unsigned& nx) {
;     ...
;     for (;;) {
;         sum = 0u; cnt = 0u; mine = 0u;
; #pragma unroll
;         for (unsigned j = 0; j < 16; ++j) { const unsigned c = xb_ld(&bar[XB_XCNT(j)]); sum += c; cnt += (c > 0u) ? 1u : 0u; mine = (j == x) ? c : mine; }
;         if (sum == G) break;
;         __builtin_amdgcn_s_sleep(1);
;         if ((++sp & 255u) == 0u) { if (xb_ld(&bar[XB_TMO])) break; if (sp > XB_SPIN_CAP) { atomicAdd(&bar[XB_TMO], 1u); break; } }
;     }
.LBB0_1806:
	global_load_dword v15, v16, s[8:9] sc1
	s_waitcnt lgkmcnt(0)
	global_load_dword v0, v16, s[10:11] sc1
	global_load_dword v1, v16, s[12:13] sc1
	global_load_dword v2, v16, s[14:15] sc1
	global_load_dword v3, v16, s[16:17] sc1
	global_load_dword v4, v16, s[18:19] sc1
	global_load_dword v5, v16, s[20:21] sc1
	global_load_dword v6, v16, s[22:23] sc1
	global_load_dword v7, v16, s[24:25] sc1
	global_load_dword v8, v16, s[26:27] sc1
	global_load_dword v9, v16, s[28:29] sc1
	global_load_dword v10, v16, s[30:31] sc1
	global_load_dword v11, v16, s[34:35] sc1
	global_load_dword v12, v16, s[36:37] sc1
	global_load_dword v13, v16, s[38:39] sc1
	global_load_dword v14, v16, s[40:41] sc1
	s_mov_b64 s[42:43], -1
	s_mov_b64 s[44:45], -1
	s_waitcnt vmcnt(14)
	v_add_u32_e32 v17, v0, v15
	s_waitcnt vmcnt(13)
	v_add_u32_e32 v17, v17, v1
	s_waitcnt vmcnt(12)
	v_add_u32_e32 v17, v17, v2
	s_waitcnt vmcnt(11)
	v_add_u32_e32 v17, v17, v3
	s_waitcnt vmcnt(10)
	v_add_u32_e32 v17, v17, v4
	s_waitcnt vmcnt(9)
	v_add_u32_e32 v17, v17, v5
	s_waitcnt vmcnt(8)
	v_add_u32_e32 v17, v17, v6
	s_waitcnt vmcnt(7)
	v_add_u32_e32 v17, v17, v7
	s_waitcnt vmcnt(6)
	v_add_u32_e32 v17, v17, v8
	s_waitcnt vmcnt(5)
	v_add_u32_e32 v17, v17, v9
	s_waitcnt vmcnt(4)
	v_add_u32_e32 v17, v17, v10
	s_waitcnt vmcnt(3)
	v_add_u32_e32 v17, v17, v11
	s_waitcnt vmcnt(2)
	v_add_u32_e32 v17, v17, v12
	s_waitcnt vmcnt(1)
	v_add_u32_e32 v17, v17, v13
	s_waitcnt vmcnt(0)
	v_add_u32_e32 v17, v17, v14
	v_cmp_eq_u32_e32 vcc, s3, v17
	s_cbranch_vccnz .LBB0_1805
	s_and_b32 s42, s33, 0xff
	s_cmp_eq_u32 s42, 0
	s_mov_b64 s[42:43], -1
	s_mov_b64 s[52:53], -1
	s_cbranch_scc1 .LBB0_1810
	s_and_b64 vcc, exec, s[52:53]
	s_cbranch_vccz .LBB0_1805

; __device__ __forceinline__ unsigned xb_ld(unsigned* p)              { return __hip_atomic_load(p, __ATOMIC_RELAXED, __HIP_MEMORY_SCOPE_AGENT); }
; __device__ __forceinline__ unsigned xb_add(unsigned* p, unsigned v) { return __hip_atomic_fetch_add(p, v, __ATOMIC_RELAXED, __HIP_MEMORY_SCOPE_AGENT); }
; #define XB_SPIN(cond, bar) do { unsigned _sp = 0; while (cond) { __builtin_amdgcn_s_sleep(1); \
;     if ((++_sp & 255u) == 0u) { if (xb_ld(&(bar)[XB_TMO])) break; if (_sp > XB_SPIN_CAP) { atomicAdd(&(bar)[XB_TMO], 1u); break; } } } } while (0)
; __device__ __forceinline__ void xcd_barrier(const XcdBarrier& b) {
;     ...
;             const unsigned og = xb_add(&bar[XB_TOP], 1u);
;             const unsigned tg = og / nx;
;             if (og + 1u == (tg + 1u) * nx) xb_add(&bar[XB_TOPGEN], 1u);
;             else XB_SPIN(xb_ld(&bar[XB_TOPGEN]) == tg, bar);
;             __builtin_amdgcn_fence(__ATOMIC_ACQUIRE, "agent");
;             xb_add(&bar[XB_XGEN(b.x)], 1u);
;             asm volatile("s_waitcnt vmcnt(0)" ::: "memory");
;         } else {
;             XB_SPIN(xb_ld(&bar[XB_XGEN(b.x)]) == gen, bar);
.LBB0_1824:
	s_and_b32 s22, s3, 0xff
	s_mov_b64 s[20:21], -1
	s_cmp_lg_u32 s22, 0
	s_mov_b64 s[24:25], -1
	s_cbranch_scc0 .LBB0_1827
	s_and_b64 vcc, exec, s[24:25]
	s_cbranch_vccz .LBB0_1823

; __device__ __forceinline__ unsigned xb_ld(unsigned* p)              { return __hip_atomic_load(p, __ATOMIC_RELAXED, __HIP_MEMORY_SCOPE_AGENT); }
; __device__ __forceinline__ unsigned xb_add(unsigned* p, unsigned v) { return __hip_atomic_fetch_add(p, v, __ATOMIC_RELAXED, __HIP_MEMORY_SCOPE_AGENT); }
; #define XB_SPIN(cond, bar) do { unsigned _sp = 0; while (cond) { __builtin_amdgcn_s_sleep(1); \
;     if ((++_sp & 255u) == 0u) { if (xb_ld(&(bar)[XB_TMO])) break; if (_sp > XB_SPIN_CAP) { atomicAdd(&(bar)[XB_TMO], 1u); break; } } } } while (0)
; __device__ __forceinline__ void xcd_barrier(const XcdBarrier& b) {
;     ...
;             const unsigned og = xb_add(&bar[XB_TOP], 1u);
;             const unsigned tg = og / nx;
;             if (og + 1u == (tg + 1u) * nx) xb_add(&bar[XB_TOPGEN], 1u);
;             else XB_SPIN(xb_ld(&bar[XB_TOPGEN]) == tg, bar);
;             __builtin_amdgcn_fence(__ATOMIC_ACQUIRE, "agent");
;             xb_add(&bar[XB_XGEN(b.x)], 1u);
;             asm volatile("s_waitcnt vmcnt(0)" ::: "memory");
;         } else {
;             XB_SPIN(xb_ld(&bar[XB_XGEN(b.x)]) == gen, bar);
.LBB0_1841:
	s_and_b32 s20, s3, 0xff
	s_cmp_lg_u32 s20, 0
	s_mov_b64 s[22:23], -1
	s_cbranch_scc0 .LBB0_1844
	s_mov_b64 s[24:25], -1
	s_and_b64 vcc, exec, s[22:23]
	s_cbranch_vccz .LBB0_1840
